# P1 de-phasing: workgroups with bit 3 of the block index set start the in-projection tiles about 10 us later (3 x s_sleep 127), so the two halves' HBM-write-bound epilogues interleave with the other ha
# speedup vs baseline: 1.0152x; 1.0072x over previous
.LBB0_107:
	v_writelane_b32 v254, s59, 20
	v_writelane_b32 v254, s60, 21
	s_nop 1
	v_writelane_b32 v254, s61, 22
	s_or_b64 exec, exec, s[0:1]
	s_add_u32 s56, s90, 0x5f6ea00
	s_addc_u32 s57, s91, 0
	s_add_u32 s40, s90, 0x3eeea00
	s_addc_u32 s41, s91, 0
	s_add_u32 s96, s90, 0x6faea00
	s_addc_u32 s97, s91, 0
	s_add_u32 s0, s90, 0x7feea00
	s_addc_u32 s1, s91, 0
	v_writelane_b32 v254, s0, 23
	v_mov_b32_e32 v12, v0
	s_waitcnt lgkmcnt(0)
	v_writelane_b32 v254, s1, 24
	s_add_u32 s0, s90, 0x902ea00
	s_addc_u32 s1, s91, 0
	v_writelane_b32 v254, s0, 25
	s_add_u32 s94, s90, 0x1e6ea00
	s_addc_u32 s95, s91, 0
	v_writelane_b32 v254, s1, 26
	s_barrier
	v_readlane_b32 s27, v254, 20
	s_bitcmp0_b32 s27, 3
	s_cbranch_scc1 .Lstg1_done
	s_sleep 127
	s_sleep 127
	s_sleep 127
.Lstg1_done:
	s_cmpk_lt_i32 s27, 0x100
	s_cselect_b64 s[0:1], -1, 0
	v_writelane_b32 v254, s0, 27
	s_cmpk_gt_i32 s27, 0xff
	s_nop 0
	v_writelane_b32 v254, s1, 28
	s_cbranch_scc1 .LBB0_165
	v_ashrrev_i32_e32 v8, 6, v12
	v_lshlrev_b32_e32 v2, 7, v8
	v_ashrrev_i32_e32 v3, 31, v2
	v_lshlrev_b64 v[6:7], 1, v[2:3]
	s_movk_i32 s0, 0x3000
	v_lshl_add_u64 v[4:5], s[94:95], 0, v[6:7]
	v_and_b32_e32 v2, 48, v12
	v_mov_b32_e32 v3, 0
	v_lshl_add_u64 v[6:7], s[90:91], 0, v[6:7]
	v_mul_lo_u32 v8, v8, s0
	s_mov_b32 s5, 0x2aaaaaab
	v_lshl_add_u64 v[4:5], v[4:5], 0, v[2:3]
	v_lshl_add_u64 v[6:7], v[6:7], 0, v[2:3]
	v_add3_u32 v2, 16, v8, v2
	v_mul_hi_i32 v8, v12, s5
	v_lshrrev_b32_e32 v10, 31, v8
	v_ashrrev_i32_e32 v8, 3, v8
	v_add_u32_e32 v11, v8, v10
	v_mul_lo_u32 v8, v11, 48
	s_movk_i32 s4, 0x180
	v_sub_u32_e32 v8, v12, v8
	v_lshlrev_b32_e32 v13, 1, v8
	v_mul_lo_u32 v10, v11, s4
	v_lshlrev_b32_e32 v8, 3, v8
	v_add3_u32 v24, 16, v10, v8
	v_add_u32_e32 v10, 0x200, v12
	v_mul_hi_i32 v15, v10, s5
	v_lshrrev_b32_e32 v16, 31, v15
	v_ashrrev_i32_e32 v15, 3, v15
	v_add_u32_e32 v27, v15, v16
	v_mul_lo_u32 v15, v27, 48
	v_sub_u32_e32 v10, v10, v15
	v_and_b32_e32 v9, 15, v12
	v_lshlrev_b32_e32 v28, 1, v10
	v_mul_lo_u32 v15, v27, s4
	v_lshlrev_b32_e32 v10, 3, v10
	v_add_u32_e32 v12, 0x400, v12
	s_add_u32 s0, s80, 0xd0
	v_add3_u32 v29, 16, v15, v10
	v_mul_hi_i32 v15, v12, s5
	s_addc_u32 s1, s81, 0
	v_lshrrev_b32_e32 v16, 31, v15
	v_ashrrev_i32_e32 v15, 3, v15
	v_add_u32_e32 v32, v15, v16
	s_add_u32 s10, s88, 0x829c000
	v_mul_lo_u32 v15, v32, 48
	s_addc_u32 s11, s89, 0
	v_sub_u32_e32 v12, v12, v15
	s_add_u32 s12, s88, 0x821c000
	v_lshlrev_b32_e32 v33, 1, v12
	v_mul_lo_u32 v15, v32, s4
	v_lshlrev_b32_e32 v12, 3, v12
	s_addc_u32 s13, s89, 0
	v_mul_u32_u24_e32 v14, 0x180, v9
	v_and_b32_e32 v8, 15, v11
	v_and_b32_e32 v10, 15, v27
	v_add3_u32 v34, 16, v15, v12
	v_and_b32_e32 v12, 15, v32
	s_add_u32 s14, s88, 0x871e000
	v_add_u32_e32 v25, 0x12000, v24
	v_add_u32_e32 v26, 0x15000, v24
	v_cmp_lt_u32_e64 s[2:3], 12, v8
	v_add_u32_e32 v8, -13, v8
	v_add_u32_e32 v30, 0x12000, v29
	v_add_u32_e32 v31, 0x15000, v29
	v_cmp_lt_u32_e64 s[6:7], 12, v10
	v_add_u32_e32 v10, -13, v10
	v_add_u32_e32 v35, 0x12000, v34
	v_add_u32_e32 v36, 0x15000, v34
	v_cmp_lt_u32_e64 s[8:9], 12, v12
	v_add_u32_e32 v12, -13, v12
	s_addc_u32 s15, s89, 0
	s_mov_b32 s4, 0x8000
	v_add_u32_e32 v37, v2, v14
	s_movk_i32 s5, 0x1ff
	s_movk_i32 s24, 0x5ff
	s_movk_i32 s25, 0x7ff
	s_movk_i32 s26, 0x9ff
	s_branch .LBB0_110
